# full-line MIN/UP stores with the nt (streaming) cache policy: UP epilogue faster and the following DOWN GEMM no slower
# speedup vs baseline: 1.0126x; 1.0126x over previous
; __device__ __forceinline__ unsigned cvt_pk_bf16(float lo, float hi) { unsigned r; asm volatile("v_cvt_pk_bf16_f32 %0, %1, %2" : "=v"(r) : "v"(lo), "v"(hi)); return r; }
;     __device__ __forceinline__ void operator()(const f32x4 (&acc)[2][2][4][2], const Unit& u, int wr, int wc, int fr, int fq) const {
;     ...
;                 for (int bj = 0; bj < 2; ++bj) { f32x4 v0 = acc[ai][bj][m][0] * rs, v1 = acc[ai][bj][m][1] * rs;
;                     if (mode == 2) {
; #pragma unroll
;                         for (int e = 0; e < 4; ++e) { float a = fmaxf(v0[e], 0.f), b = fmaxf(v1[e], 0.f); v0[e] = a * a; v1[e] = b * b; } }
;                     if (mode == 1 && colt >= 2048) {
; #pragma unroll
;                         for (int e = 0; e < 4; ++e) { v0[e] = __builtin_amdgcn_rcpf(1.0f + __builtin_amdgcn_exp2f(-1.4426950408889634f * v0[e])); v1[e] = __builtin_amdgcn_rcpf(1.0f + __builtin_amdgcn_exp2f(-1.4426950408889634f * v1[e])); } }
;                     u32x4 w; w.x = cvt_pk_bf16(v0[0], v0[1]); w.y = cvt_pk_bf16(v0[2], v0[3]); w.z = cvt_pk_bf16(v1[0], v1[1]); w.w = cvt_pk_bf16(v1[2], v1[3]);
;                     *(u32x4*)(rowp + bj * HALF) = w; }
.LBB0_368:
	v_cvt_pk_bf16_f32 v90, v90, v91
	v_cvt_pk_bf16_f32 v91, v86, v87
	v_cvt_pk_bf16_f32 v92, v82, v83
	v_cvt_pk_bf16_f32 v93, v88, v89
	s_mov_b32 vcc_lo, 0xff00ff00
	s_mov_b32 vcc_hi, 0xff00ff00
	v_mov_b32_dpp v222, v218 row_ror:8 row_mask:0xf bank_mask:0xf
	v_mov_b32_dpp v223, v219 row_ror:8 row_mask:0xf bank_mask:0xf
	v_mov_b32_dpp v224, v220 row_ror:8 row_mask:0xf bank_mask:0xf
	v_mov_b32_dpp v225, v221 row_ror:8 row_mask:0xf bank_mask:0xf
	v_mov_b32_dpp v242, v90 row_ror:8 row_mask:0xf bank_mask:0xf
	v_mov_b32_dpp v243, v91 row_ror:8 row_mask:0xf bank_mask:0xf
	v_mov_b32_dpp v244, v92 row_ror:8 row_mask:0xf bank_mask:0xf
	v_mov_b32_dpp v245, v93 row_ror:8 row_mask:0xf bank_mask:0xf
	v_lshl_add_u64 v[246:247], v[84:85], 0, v[214:215]
	v_lshl_add_u64 v[248:249], v[84:85], 0, v[216:217]
	v_cndmask_b32_e32 v242, v218, v242, vcc
	v_cndmask_b32_e32 v243, v219, v243, vcc
	v_cndmask_b32_e32 v244, v220, v244, vcc
	v_cndmask_b32_e32 v245, v221, v245, vcc
	v_cndmask_b32_e32 v222, v222, v90, vcc
	v_cndmask_b32_e32 v223, v223, v91, vcc
	v_cndmask_b32_e32 v224, v224, v92, vcc
	v_cndmask_b32_e32 v225, v225, v93, vcc
	global_store_dwordx4 v[246:247], v[242:245], off nt
	global_store_dwordx4 v[248:249], v[222:225], off nt
	s_and_b64 vcc, exec, s[42:43]
	s_nop 1
	v_cvt_f32_u32_e32 v83, v195
	v_cvt_f32_u32_e32 v82, v194
	v_fmamk_f32 v82, v83, 0x4f800000, v82
	v_fmamk_f32 v82, v82, 0x30800000, v229
	v_rsq_f32_e32 v82, v82
	s_nop 0
	v_pk_mul_f32 v[86:87], v[128:129], v[82:83] op_sel_hi:[1,0]
	v_pk_mul_f32 v[90:91], v[126:127], v[82:83] op_sel_hi:[1,0]
	v_pk_mul_f32 v[88:89], v[124:125], v[82:83] op_sel_hi:[1,0]
	v_pk_mul_f32 v[92:93], v[122:123], v[82:83] op_sel_hi:[1,0]
	s_cbranch_vccnz .LBB0_370
	v_max_f32_e32 v84, 0, v90
	v_max_f32_e32 v92, 0, v92
	v_max_f32_e32 v85, 0, v91
	v_max_f32_e32 v93, 0, v93
	v_max_f32_e32 v86, 0, v86
	v_max_f32_e32 v88, 0, v88
	v_max_f32_e32 v87, 0, v87
	v_max_f32_e32 v89, 0, v89
	v_pk_mul_f32 v[90:91], v[84:85], v[84:85]
	v_pk_mul_f32 v[86:87], v[86:87], v[86:87]
	v_pk_mul_f32 v[92:93], v[92:93], v[92:93]
	v_pk_mul_f32 v[88:89], v[88:89], v[88:89]

; __device__ __forceinline__ unsigned cvt_pk_bf16(float lo, float hi) { unsigned r; asm volatile("v_cvt_pk_bf16_f32 %0, %1, %2" : "=v"(r) : "v"(lo), "v"(hi)); return r; }
;     __device__ __forceinline__ void operator()(const f32x4 (&acc)[2][2][4][2], const Unit& u, int wr, int wc, int fr, int fq) const {
;     ...
;                 for (int bj = 0; bj < 2; ++bj) { f32x4 v0 = acc[ai][bj][m][0] * rs, v1 = acc[ai][bj][m][1] * rs;
;                     if (mode == 2) {
; #pragma unroll
;                         for (int e = 0; e < 4; ++e) { float a = fmaxf(v0[e], 0.f), b = fmaxf(v1[e], 0.f); v0[e] = a * a; v1[e] = b * b; } }
;                     if (mode == 1 && colt >= 2048) {
; #pragma unroll
;                         for (int e = 0; e < 4; ++e) { v0[e] = __builtin_amdgcn_rcpf(1.0f + __builtin_amdgcn_exp2f(-1.4426950408889634f * v0[e])); v1[e] = __builtin_amdgcn_rcpf(1.0f + __builtin_amdgcn_exp2f(-1.4426950408889634f * v1[e])); } }
;                     u32x4 w; w.x = cvt_pk_bf16(v0[0], v0[1]); w.y = cvt_pk_bf16(v0[2], v0[3]); w.z = cvt_pk_bf16(v1[0], v1[1]); w.w = cvt_pk_bf16(v1[2], v1[3]);
;                     *(u32x4*)(rowp + bj * HALF) = w; }
.LBB0_376:
	v_cvt_pk_bf16_f32 v90, v90, v91
	v_cvt_pk_bf16_f32 v91, v86, v87
	v_cvt_pk_bf16_f32 v92, v82, v83
	v_cvt_pk_bf16_f32 v93, v88, v89
	s_mov_b32 vcc_lo, 0xff00ff00
	s_mov_b32 vcc_hi, 0xff00ff00
	v_mov_b32_dpp v222, v218 row_ror:8 row_mask:0xf bank_mask:0xf
	v_mov_b32_dpp v223, v219 row_ror:8 row_mask:0xf bank_mask:0xf
	v_mov_b32_dpp v224, v220 row_ror:8 row_mask:0xf bank_mask:0xf
	v_mov_b32_dpp v225, v221 row_ror:8 row_mask:0xf bank_mask:0xf
	v_mov_b32_dpp v242, v90 row_ror:8 row_mask:0xf bank_mask:0xf
	v_mov_b32_dpp v243, v91 row_ror:8 row_mask:0xf bank_mask:0xf
	v_mov_b32_dpp v244, v92 row_ror:8 row_mask:0xf bank_mask:0xf
	v_mov_b32_dpp v245, v93 row_ror:8 row_mask:0xf bank_mask:0xf
	v_lshl_add_u64 v[246:247], v[208:209], 0, v[214:215]
	v_lshl_add_u64 v[248:249], v[208:209], 0, v[216:217]
	v_cndmask_b32_e32 v242, v218, v242, vcc
	v_cndmask_b32_e32 v243, v219, v243, vcc
	v_cndmask_b32_e32 v244, v220, v244, vcc
	v_cndmask_b32_e32 v245, v221, v245, vcc
	v_cndmask_b32_e32 v222, v222, v90, vcc
	v_cndmask_b32_e32 v223, v223, v91, vcc
	v_cndmask_b32_e32 v224, v224, v92, vcc
	v_cndmask_b32_e32 v225, v225, v93, vcc
	global_store_dwordx4 v[246:247], v[242:245], off nt
	global_store_dwordx4 v[248:249], v[222:225], off nt
	v_lshl_add_u64 v[208:209], v[208:209], 0, v[210:211]
	s_and_b64 vcc, exec, s[42:43]
	s_nop 1
	v_cvt_f32_u32_e32 v83, v197
	v_cvt_f32_u32_e32 v82, v196
	v_fmamk_f32 v82, v83, 0x4f800000, v82
	v_fmamk_f32 v82, v82, 0x30800000, v229
	v_rsq_f32_e32 v82, v82
	s_nop 0
	v_pk_mul_f32 v[86:87], v[110:111], v[82:83] op_sel_hi:[1,0]
	v_pk_mul_f32 v[90:91], v[108:109], v[82:83] op_sel_hi:[1,0]
	v_pk_mul_f32 v[88:89], v[106:107], v[82:83] op_sel_hi:[1,0]
	v_pk_mul_f32 v[92:93], v[104:105], v[82:83] op_sel_hi:[1,0]
	s_cbranch_vccnz .LBB0_378
	v_max_f32_e32 v84, 0, v90
	v_max_f32_e32 v92, 0, v92
	v_max_f32_e32 v85, 0, v91
	v_max_f32_e32 v93, 0, v93
	v_max_f32_e32 v86, 0, v86
	v_max_f32_e32 v88, 0, v88
	v_max_f32_e32 v87, 0, v87
	v_max_f32_e32 v89, 0, v89
	v_pk_mul_f32 v[90:91], v[84:85], v[84:85]
	v_pk_mul_f32 v[86:87], v[86:87], v[86:87]
	v_pk_mul_f32 v[92:93], v[92:93], v[92:93]
	v_pk_mul_f32 v[88:89], v[88:89], v[88:89]

; __device__ __forceinline__ unsigned cvt_pk_bf16(float lo, float hi) { unsigned r; asm volatile("v_cvt_pk_bf16_f32 %0, %1, %2" : "=v"(r) : "v"(lo), "v"(hi)); return r; }
;     __device__ __forceinline__ void operator()(const f32x4 (&acc)[2][2][4][2], const Unit& u, int wr, int wc, int fr, int fq) const {
;     ...
;                 for (int bj = 0; bj < 2; ++bj) { f32x4 v0 = acc[ai][bj][m][0] * rs, v1 = acc[ai][bj][m][1] * rs;
;                     if (mode == 2) {
; #pragma unroll
;                         for (int e = 0; e < 4; ++e) { float a = fmaxf(v0[e], 0.f), b = fmaxf(v1[e], 0.f); v0[e] = a * a; v1[e] = b * b; } }
;                     if (mode == 1 && colt >= 2048) {
; #pragma unroll
;                         for (int e = 0; e < 4; ++e) { v0[e] = __builtin_amdgcn_rcpf(1.0f + __builtin_amdgcn_exp2f(-1.4426950408889634f * v0[e])); v1[e] = __builtin_amdgcn_rcpf(1.0f + __builtin_amdgcn_exp2f(-1.4426950408889634f * v1[e])); } }
;                     u32x4 w; w.x = cvt_pk_bf16(v0[0], v0[1]); w.y = cvt_pk_bf16(v0[2], v0[3]); w.z = cvt_pk_bf16(v1[0], v1[1]); w.w = cvt_pk_bf16(v1[2], v1[3]);
;                     *(u32x4*)(rowp + bj * HALF) = w; }
.LBB0_384:
	v_cvt_pk_bf16_f32 v90, v90, v91
	v_cvt_pk_bf16_f32 v91, v86, v87
	v_cvt_pk_bf16_f32 v92, v82, v83
	v_cvt_pk_bf16_f32 v93, v88, v89
	s_mov_b32 vcc_lo, 0xff00ff00
	s_mov_b32 vcc_hi, 0xff00ff00
	v_mov_b32_dpp v222, v218 row_ror:8 row_mask:0xf bank_mask:0xf
	v_mov_b32_dpp v223, v219 row_ror:8 row_mask:0xf bank_mask:0xf
	v_mov_b32_dpp v224, v220 row_ror:8 row_mask:0xf bank_mask:0xf
	v_mov_b32_dpp v225, v221 row_ror:8 row_mask:0xf bank_mask:0xf
	v_mov_b32_dpp v242, v90 row_ror:8 row_mask:0xf bank_mask:0xf
	v_mov_b32_dpp v243, v91 row_ror:8 row_mask:0xf bank_mask:0xf
	v_mov_b32_dpp v244, v92 row_ror:8 row_mask:0xf bank_mask:0xf
	v_mov_b32_dpp v245, v93 row_ror:8 row_mask:0xf bank_mask:0xf
	v_lshl_add_u64 v[246:247], v[208:209], 0, v[214:215]
	v_lshl_add_u64 v[248:249], v[208:209], 0, v[216:217]
	v_cndmask_b32_e32 v242, v218, v242, vcc
	v_cndmask_b32_e32 v243, v219, v243, vcc
	v_cndmask_b32_e32 v244, v220, v244, vcc
	v_cndmask_b32_e32 v245, v221, v245, vcc
	v_cndmask_b32_e32 v222, v222, v90, vcc
	v_cndmask_b32_e32 v223, v223, v91, vcc
	v_cndmask_b32_e32 v224, v224, v92, vcc
	v_cndmask_b32_e32 v225, v225, v93, vcc
	global_store_dwordx4 v[246:247], v[242:245], off nt
	global_store_dwordx4 v[248:249], v[222:225], off nt
	v_lshl_add_u64 v[208:209], v[208:209], 0, v[210:211]
	s_and_b64 vcc, exec, s[42:43]
	s_nop 1
	v_cvt_f32_u32_e32 v83, v199
	v_cvt_f32_u32_e32 v82, v198
	v_fmamk_f32 v82, v83, 0x4f800000, v82
	v_fmamk_f32 v82, v82, 0x30800000, v229
	v_rsq_f32_e32 v82, v82
	s_nop 0
	v_pk_mul_f32 v[86:87], v[78:79], v[82:83] op_sel_hi:[1,0]
	v_pk_mul_f32 v[90:91], v[76:77], v[82:83] op_sel_hi:[1,0]
	v_pk_mul_f32 v[88:89], v[74:75], v[82:83] op_sel_hi:[1,0]
	v_pk_mul_f32 v[92:93], v[72:73], v[82:83] op_sel_hi:[1,0]
	s_cbranch_vccnz .LBB0_386
	v_max_f32_e32 v84, 0, v90
	v_max_f32_e32 v92, 0, v92
	v_max_f32_e32 v85, 0, v91
	v_max_f32_e32 v93, 0, v93
	v_max_f32_e32 v86, 0, v86
	v_max_f32_e32 v88, 0, v88
	v_max_f32_e32 v87, 0, v87
	v_max_f32_e32 v89, 0, v89
	v_pk_mul_f32 v[90:91], v[84:85], v[84:85]
	v_pk_mul_f32 v[86:87], v[86:87], v[86:87]
	v_pk_mul_f32 v[92:93], v[92:93], v[92:93]
	v_pk_mul_f32 v[88:89], v[88:89], v[88:89]

; __device__ __forceinline__ unsigned cvt_pk_bf16(float lo, float hi) { unsigned r; asm volatile("v_cvt_pk_bf16_f32 %0, %1, %2" : "=v"(r) : "v"(lo), "v"(hi)); return r; }
;     __device__ __forceinline__ void operator()(const f32x4 (&acc)[2][2][4][2], const Unit& u, int wr, int wc, int fr, int fq) const {
;     ...
;                 for (int bj = 0; bj < 2; ++bj) { f32x4 v0 = acc[ai][bj][m][0] * rs, v1 = acc[ai][bj][m][1] * rs;
;                     if (mode == 2) {
; #pragma unroll
;                         for (int e = 0; e < 4; ++e) { float a = fmaxf(v0[e], 0.f), b = fmaxf(v1[e], 0.f); v0[e] = a * a; v1[e] = b * b; } }
;                     if (mode == 1 && colt >= 2048) {
; #pragma unroll
;                         for (int e = 0; e < 4; ++e) { v0[e] = __builtin_amdgcn_rcpf(1.0f + __builtin_amdgcn_exp2f(-1.4426950408889634f * v0[e])); v1[e] = __builtin_amdgcn_rcpf(1.0f + __builtin_amdgcn_exp2f(-1.4426950408889634f * v1[e])); } }
;                     u32x4 w; w.x = cvt_pk_bf16(v0[0], v0[1]); w.y = cvt_pk_bf16(v0[2], v0[3]); w.z = cvt_pk_bf16(v1[0], v1[1]); w.w = cvt_pk_bf16(v1[2], v1[3]);
;                     *(u32x4*)(rowp + bj * HALF) = w; }
.LBB0_392:
	v_cvt_pk_bf16_f32 v90, v90, v91
	v_cvt_pk_bf16_f32 v91, v86, v87
	v_cvt_pk_bf16_f32 v92, v82, v83
	v_cvt_pk_bf16_f32 v93, v88, v89
	s_mov_b32 vcc_lo, 0xff00ff00
	s_mov_b32 vcc_hi, 0xff00ff00
	v_mov_b32_dpp v222, v218 row_ror:8 row_mask:0xf bank_mask:0xf
	v_mov_b32_dpp v223, v219 row_ror:8 row_mask:0xf bank_mask:0xf
	v_mov_b32_dpp v224, v220 row_ror:8 row_mask:0xf bank_mask:0xf
	v_mov_b32_dpp v225, v221 row_ror:8 row_mask:0xf bank_mask:0xf
	v_mov_b32_dpp v242, v90 row_ror:8 row_mask:0xf bank_mask:0xf
	v_mov_b32_dpp v243, v91 row_ror:8 row_mask:0xf bank_mask:0xf
	v_mov_b32_dpp v244, v92 row_ror:8 row_mask:0xf bank_mask:0xf
	v_mov_b32_dpp v245, v93 row_ror:8 row_mask:0xf bank_mask:0xf
	v_lshl_add_u64 v[246:247], v[208:209], 0, v[214:215]
	v_lshl_add_u64 v[248:249], v[208:209], 0, v[216:217]
	v_cndmask_b32_e32 v242, v218, v242, vcc
	v_cndmask_b32_e32 v243, v219, v243, vcc
	v_cndmask_b32_e32 v244, v220, v244, vcc
	v_cndmask_b32_e32 v245, v221, v245, vcc
	v_cndmask_b32_e32 v222, v222, v90, vcc
	v_cndmask_b32_e32 v223, v223, v91, vcc
	v_cndmask_b32_e32 v224, v224, v92, vcc
	v_cndmask_b32_e32 v225, v225, v93, vcc
	global_store_dwordx4 v[246:247], v[242:245], off nt
	global_store_dwordx4 v[248:249], v[222:225], off nt
	v_lshl_add_u64 v[208:209], v[208:209], 0, v[212:213]
	s_and_b64 vcc, exec, s[42:43]
	s_nop 1
	v_cvt_f32_u32_e32 v83, v201
	v_cvt_f32_u32_e32 v82, v200
	v_fmamk_f32 v82, v83, 0x4f800000, v82
	v_fmamk_f32 v82, v82, 0x30800000, v229
	v_rsq_f32_e32 v82, v82
	s_nop 0
	v_pk_mul_f32 v[86:87], v[62:63], v[82:83] op_sel_hi:[1,0]
	v_pk_mul_f32 v[90:91], v[60:61], v[82:83] op_sel_hi:[1,0]
	v_pk_mul_f32 v[88:89], v[58:59], v[82:83] op_sel_hi:[1,0]
	v_pk_mul_f32 v[92:93], v[56:57], v[82:83] op_sel_hi:[1,0]
	s_cbranch_vccnz .LBB0_394
	v_max_f32_e32 v84, 0, v90
	v_max_f32_e32 v92, 0, v92
	v_max_f32_e32 v85, 0, v91
	v_max_f32_e32 v93, 0, v93
	v_max_f32_e32 v86, 0, v86
	v_max_f32_e32 v88, 0, v88
	v_max_f32_e32 v87, 0, v87
	v_max_f32_e32 v89, 0, v89
	v_pk_mul_f32 v[90:91], v[84:85], v[84:85]
	v_pk_mul_f32 v[86:87], v[86:87], v[86:87]
	v_pk_mul_f32 v[92:93], v[92:93], v[92:93]
	v_pk_mul_f32 v[88:89], v[88:89], v[88:89]

; __device__ __forceinline__ unsigned cvt_pk_bf16(float lo, float hi) { unsigned r; asm volatile("v_cvt_pk_bf16_f32 %0, %1, %2" : "=v"(r) : "v"(lo), "v"(hi)); return r; }
;     __device__ __forceinline__ void operator()(const f32x4 (&acc)[2][2][4][2], const Unit& u, int wr, int wc, int fr, int fq) const {
;     ...
;                 for (int bj = 0; bj < 2; ++bj) { f32x4 v0 = acc[ai][bj][m][0] * rs, v1 = acc[ai][bj][m][1] * rs;
;                     if (mode == 2) {
; #pragma unroll
;                         for (int e = 0; e < 4; ++e) { float a = fmaxf(v0[e], 0.f), b = fmaxf(v1[e], 0.f); v0[e] = a * a; v1[e] = b * b; } }
;                     if (mode == 1 && colt >= 2048) {
; #pragma unroll
;                         for (int e = 0; e < 4; ++e) { v0[e] = __builtin_amdgcn_rcpf(1.0f + __builtin_amdgcn_exp2f(-1.4426950408889634f * v0[e])); v1[e] = __builtin_amdgcn_rcpf(1.0f + __builtin_amdgcn_exp2f(-1.4426950408889634f * v1[e])); } }
;                     u32x4 w; w.x = cvt_pk_bf16(v0[0], v0[1]); w.y = cvt_pk_bf16(v0[2], v0[3]); w.z = cvt_pk_bf16(v1[0], v1[1]); w.w = cvt_pk_bf16(v1[2], v1[3]);
;                     *(u32x4*)(rowp + bj * HALF) = w; }
.LBB0_400:
	v_cvt_pk_bf16_f32 v90, v90, v91
	v_cvt_pk_bf16_f32 v91, v86, v87
	v_cvt_pk_bf16_f32 v92, v82, v83
	v_cvt_pk_bf16_f32 v93, v88, v89
	s_mov_b32 vcc_lo, 0xff00ff00
	s_mov_b32 vcc_hi, 0xff00ff00
	v_mov_b32_dpp v222, v218 row_ror:8 row_mask:0xf bank_mask:0xf
	v_mov_b32_dpp v223, v219 row_ror:8 row_mask:0xf bank_mask:0xf
	v_mov_b32_dpp v224, v220 row_ror:8 row_mask:0xf bank_mask:0xf
	v_mov_b32_dpp v225, v221 row_ror:8 row_mask:0xf bank_mask:0xf
	v_mov_b32_dpp v242, v90 row_ror:8 row_mask:0xf bank_mask:0xf
	v_mov_b32_dpp v243, v91 row_ror:8 row_mask:0xf bank_mask:0xf
	v_mov_b32_dpp v244, v92 row_ror:8 row_mask:0xf bank_mask:0xf
	v_mov_b32_dpp v245, v93 row_ror:8 row_mask:0xf bank_mask:0xf
	v_lshl_add_u64 v[246:247], v[208:209], 0, v[214:215]
	v_lshl_add_u64 v[248:249], v[208:209], 0, v[216:217]
	v_cndmask_b32_e32 v242, v218, v242, vcc
	v_cndmask_b32_e32 v243, v219, v243, vcc
	v_cndmask_b32_e32 v244, v220, v244, vcc
	v_cndmask_b32_e32 v245, v221, v245, vcc
	v_cndmask_b32_e32 v222, v222, v90, vcc
	v_cndmask_b32_e32 v223, v223, v91, vcc
	v_cndmask_b32_e32 v224, v224, v92, vcc
	v_cndmask_b32_e32 v225, v225, v93, vcc
	global_store_dwordx4 v[246:247], v[242:245], off nt
	global_store_dwordx4 v[248:249], v[222:225], off nt
	v_lshl_add_u64 v[208:209], v[208:209], 0, v[210:211]
	s_and_b64 vcc, exec, s[42:43]
	s_nop 1
	v_cvt_f32_u32_e32 v83, v203
	v_cvt_f32_u32_e32 v82, v202
	v_fmamk_f32 v82, v83, 0x4f800000, v82
	v_fmamk_f32 v82, v82, 0x30800000, v229
	v_rsq_f32_e32 v82, v82
	s_nop 0
	v_pk_mul_f32 v[86:87], v[46:47], v[82:83] op_sel_hi:[1,0]
	v_pk_mul_f32 v[90:91], v[44:45], v[82:83] op_sel_hi:[1,0]
	v_pk_mul_f32 v[88:89], v[42:43], v[82:83] op_sel_hi:[1,0]
	v_pk_mul_f32 v[92:93], v[40:41], v[82:83] op_sel_hi:[1,0]
	s_cbranch_vccnz .LBB0_402
	v_max_f32_e32 v84, 0, v90
	v_max_f32_e32 v92, 0, v92
	v_max_f32_e32 v85, 0, v91
	v_max_f32_e32 v93, 0, v93
	v_max_f32_e32 v86, 0, v86
	v_max_f32_e32 v88, 0, v88
	v_max_f32_e32 v87, 0, v87
	v_max_f32_e32 v89, 0, v89
	v_pk_mul_f32 v[90:91], v[84:85], v[84:85]
	v_pk_mul_f32 v[86:87], v[86:87], v[86:87]
	v_pk_mul_f32 v[92:93], v[92:93], v[92:93]
	v_pk_mul_f32 v[88:89], v[88:89], v[88:89]

; __device__ __forceinline__ unsigned cvt_pk_bf16(float lo, float hi) { unsigned r; asm volatile("v_cvt_pk_bf16_f32 %0, %1, %2" : "=v"(r) : "v"(lo), "v"(hi)); return r; }
;     __device__ __forceinline__ void operator()(const f32x4 (&acc)[2][2][4][2], const Unit& u, int wr, int wc, int fr, int fq) const {
;     ...
;                 for (int bj = 0; bj < 2; ++bj) { f32x4 v0 = acc[ai][bj][m][0] * rs, v1 = acc[ai][bj][m][1] * rs;
;                     if (mode == 2) {
; #pragma unroll
;                         for (int e = 0; e < 4; ++e) { float a = fmaxf(v0[e], 0.f), b = fmaxf(v1[e], 0.f); v0[e] = a * a; v1[e] = b * b; } }
;                     if (mode == 1 && colt >= 2048) {
; #pragma unroll
;                         for (int e = 0; e < 4; ++e) { v0[e] = __builtin_amdgcn_rcpf(1.0f + __builtin_amdgcn_exp2f(-1.4426950408889634f * v0[e])); v1[e] = __builtin_amdgcn_rcpf(1.0f + __builtin_amdgcn_exp2f(-1.4426950408889634f * v1[e])); } }
;                     u32x4 w; w.x = cvt_pk_bf16(v0[0], v0[1]); w.y = cvt_pk_bf16(v0[2], v0[3]); w.z = cvt_pk_bf16(v1[0], v1[1]); w.w = cvt_pk_bf16(v1[2], v1[3]);
;                     *(u32x4*)(rowp + bj * HALF) = w; }
.LBB0_408:
	v_cvt_pk_bf16_f32 v90, v90, v91
	v_cvt_pk_bf16_f32 v91, v86, v87
	v_cvt_pk_bf16_f32 v92, v82, v83
	v_cvt_pk_bf16_f32 v93, v88, v89
	s_mov_b32 vcc_lo, 0xff00ff00
	s_mov_b32 vcc_hi, 0xff00ff00
	v_mov_b32_dpp v222, v218 row_ror:8 row_mask:0xf bank_mask:0xf
	v_mov_b32_dpp v223, v219 row_ror:8 row_mask:0xf bank_mask:0xf
	v_mov_b32_dpp v224, v220 row_ror:8 row_mask:0xf bank_mask:0xf
	v_mov_b32_dpp v225, v221 row_ror:8 row_mask:0xf bank_mask:0xf
	v_mov_b32_dpp v242, v90 row_ror:8 row_mask:0xf bank_mask:0xf
	v_mov_b32_dpp v243, v91 row_ror:8 row_mask:0xf bank_mask:0xf
	v_mov_b32_dpp v244, v92 row_ror:8 row_mask:0xf bank_mask:0xf
	v_mov_b32_dpp v245, v93 row_ror:8 row_mask:0xf bank_mask:0xf
	v_lshl_add_u64 v[246:247], v[208:209], 0, v[214:215]
	v_lshl_add_u64 v[248:249], v[208:209], 0, v[216:217]
	v_cndmask_b32_e32 v242, v218, v242, vcc
	v_cndmask_b32_e32 v243, v219, v243, vcc
	v_cndmask_b32_e32 v244, v220, v244, vcc
	v_cndmask_b32_e32 v245, v221, v245, vcc
	v_cndmask_b32_e32 v222, v222, v90, vcc
	v_cndmask_b32_e32 v223, v223, v91, vcc
	v_cndmask_b32_e32 v224, v224, v92, vcc
	v_cndmask_b32_e32 v225, v225, v93, vcc
	global_store_dwordx4 v[246:247], v[242:245], off nt
	global_store_dwordx4 v[248:249], v[222:225], off nt
	v_lshl_add_u64 v[208:209], v[208:209], 0, v[210:211]
	s_and_b64 vcc, exec, s[42:43]
	s_nop 1
	v_cvt_f32_u32_e32 v83, v205
	v_cvt_f32_u32_e32 v82, v204
	v_fmamk_f32 v82, v83, 0x4f800000, v82
	v_fmamk_f32 v82, v82, 0x30800000, v229
	v_rsq_f32_e32 v82, v82
	s_nop 0
	v_pk_mul_f32 v[86:87], v[30:31], v[82:83] op_sel_hi:[1,0]
	v_pk_mul_f32 v[90:91], v[28:29], v[82:83] op_sel_hi:[1,0]
	v_pk_mul_f32 v[88:89], v[26:27], v[82:83] op_sel_hi:[1,0]
	v_pk_mul_f32 v[92:93], v[24:25], v[82:83] op_sel_hi:[1,0]
	s_cbranch_vccnz .LBB0_410
	v_max_f32_e32 v84, 0, v90
	v_max_f32_e32 v92, 0, v92
	v_max_f32_e32 v85, 0, v91
	v_max_f32_e32 v93, 0, v93
	v_max_f32_e32 v86, 0, v86
	v_max_f32_e32 v88, 0, v88
	v_max_f32_e32 v87, 0, v87
	v_max_f32_e32 v89, 0, v89
	v_pk_mul_f32 v[90:91], v[84:85], v[84:85]
	v_pk_mul_f32 v[86:87], v[86:87], v[86:87]
	v_pk_mul_f32 v[92:93], v[92:93], v[92:93]
	v_pk_mul_f32 v[88:89], v[88:89], v[88:89]

; __device__ __forceinline__ unsigned cvt_pk_bf16(float lo, float hi) { unsigned r; asm volatile("v_cvt_pk_bf16_f32 %0, %1, %2" : "=v"(r) : "v"(lo), "v"(hi)); return r; }
;     __device__ __forceinline__ void operator()(const f32x4 (&acc)[2][2][4][2], const Unit& u, int wr, int wc, int fr, int fq) const {
;     ...
;                 for (int bj = 0; bj < 2; ++bj) { f32x4 v0 = acc[ai][bj][m][0] * rs, v1 = acc[ai][bj][m][1] * rs;
;                     if (mode == 2) {
; #pragma unroll
;                         for (int e = 0; e < 4; ++e) { float a = fmaxf(v0[e], 0.f), b = fmaxf(v1[e], 0.f); v0[e] = a * a; v1[e] = b * b; } }
;                     if (mode == 1 && colt >= 2048) {
; #pragma unroll
;                         for (int e = 0; e < 4; ++e) { v0[e] = __builtin_amdgcn_rcpf(1.0f + __builtin_amdgcn_exp2f(-1.4426950408889634f * v0[e])); v1[e] = __builtin_amdgcn_rcpf(1.0f + __builtin_amdgcn_exp2f(-1.4426950408889634f * v1[e])); } }
;                     u32x4 w; w.x = cvt_pk_bf16(v0[0], v0[1]); w.y = cvt_pk_bf16(v0[2], v0[3]); w.z = cvt_pk_bf16(v1[0], v1[1]); w.w = cvt_pk_bf16(v1[2], v1[3]);
;                     *(u32x4*)(rowp + bj * HALF) = w; }
.LBB0_416:
	v_cvt_pk_bf16_f32 v90, v90, v91
	v_cvt_pk_bf16_f32 v91, v86, v87
	v_cvt_pk_bf16_f32 v92, v82, v83
	v_cvt_pk_bf16_f32 v93, v88, v89
	s_mov_b32 vcc_lo, 0xff00ff00
	s_mov_b32 vcc_hi, 0xff00ff00
	v_mov_b32_dpp v222, v218 row_ror:8 row_mask:0xf bank_mask:0xf
	v_mov_b32_dpp v223, v219 row_ror:8 row_mask:0xf bank_mask:0xf
	v_mov_b32_dpp v224, v220 row_ror:8 row_mask:0xf bank_mask:0xf
	v_mov_b32_dpp v225, v221 row_ror:8 row_mask:0xf bank_mask:0xf
	v_mov_b32_dpp v242, v90 row_ror:8 row_mask:0xf bank_mask:0xf
	v_mov_b32_dpp v243, v91 row_ror:8 row_mask:0xf bank_mask:0xf
	v_mov_b32_dpp v244, v92 row_ror:8 row_mask:0xf bank_mask:0xf
	v_mov_b32_dpp v245, v93 row_ror:8 row_mask:0xf bank_mask:0xf
	v_lshl_add_u64 v[246:247], v[208:209], 0, v[214:215]
	v_lshl_add_u64 v[248:249], v[208:209], 0, v[216:217]
	v_cndmask_b32_e32 v242, v218, v242, vcc
	v_cndmask_b32_e32 v243, v219, v243, vcc
	v_cndmask_b32_e32 v244, v220, v244, vcc
	v_cndmask_b32_e32 v245, v221, v245, vcc
	v_cndmask_b32_e32 v222, v222, v90, vcc
	v_cndmask_b32_e32 v223, v223, v91, vcc
	v_cndmask_b32_e32 v224, v224, v92, vcc
	v_cndmask_b32_e32 v225, v225, v93, vcc
	global_store_dwordx4 v[246:247], v[242:245], off nt
	global_store_dwordx4 v[248:249], v[222:225], off nt
	v_lshl_add_u64 v[208:209], v[208:209], 0, v[210:211]
	s_and_b64 vcc, exec, s[42:43]
	s_nop 1
	v_cvt_f32_u32_e32 v81, v207
	v_cvt_f32_u32_e32 v80, v206
	v_fmamk_f32 v80, v81, 0x4f800000, v80
	v_fmamk_f32 v80, v80, 0x30800000, v229
	v_rsq_f32_e32 v80, v80
	s_nop 0
	v_pk_mul_f32 v[84:85], v[14:15], v[80:81] op_sel_hi:[1,0]
	v_pk_mul_f32 v[88:89], v[12:13], v[80:81] op_sel_hi:[1,0]
	v_pk_mul_f32 v[86:87], v[10:11], v[80:81] op_sel_hi:[1,0]
	v_pk_mul_f32 v[90:91], v[8:9], v[80:81] op_sel_hi:[1,0]
	s_cbranch_vccnz .LBB0_418
	v_max_f32_e32 v82, 0, v88
	v_max_f32_e32 v90, 0, v90
	v_max_f32_e32 v83, 0, v89
	v_max_f32_e32 v91, 0, v91
	v_max_f32_e32 v84, 0, v84
	v_max_f32_e32 v86, 0, v86
	v_max_f32_e32 v85, 0, v85
	v_max_f32_e32 v87, 0, v87
	v_pk_mul_f32 v[88:89], v[82:83], v[82:83]
	v_pk_mul_f32 v[84:85], v[84:85], v[84:85]
	v_pk_mul_f32 v[90:91], v[90:91], v[90:91]
	v_pk_mul_f32 v[86:87], v[86:87], v[86:87]

; __device__ __forceinline__ unsigned cvt_pk_bf16(float lo, float hi) { unsigned r; asm volatile("v_cvt_pk_bf16_f32 %0, %1, %2" : "=v"(r) : "v"(lo), "v"(hi)); return r; }
;     __device__ __forceinline__ void operator()(const f32x4 (&acc)[2][2][4][2], const Unit& u, int wr, int wc, int fr, int fq) const {
;     ...
;                 for (int bj = 0; bj < 2; ++bj) { f32x4 v0 = acc[ai][bj][m][0] * rs, v1 = acc[ai][bj][m][1] * rs;
;                     if (mode == 2) {
; #pragma unroll
;                         for (int e = 0; e < 4; ++e) { float a = fmaxf(v0[e], 0.f), b = fmaxf(v1[e], 0.f); v0[e] = a * a; v1[e] = b * b; } }
;                     if (mode == 1 && colt >= 2048) {
; #pragma unroll
;                         for (int e = 0; e < 4; ++e) { v0[e] = __builtin_amdgcn_rcpf(1.0f + __builtin_amdgcn_exp2f(-1.4426950408889634f * v0[e])); v1[e] = __builtin_amdgcn_rcpf(1.0f + __builtin_amdgcn_exp2f(-1.4426950408889634f * v1[e])); } }
;                     u32x4 w; w.x = cvt_pk_bf16(v0[0], v0[1]); w.y = cvt_pk_bf16(v0[2], v0[3]); w.z = cvt_pk_bf16(v1[0], v1[1]); w.w = cvt_pk_bf16(v1[2], v1[3]);
;                     *(u32x4*)(rowp + bj * HALF) = w; }
.LBB0_424:
	v_cvt_pk_bf16_f32 v88, v88, v89
	v_cvt_pk_bf16_f32 v89, v86, v87
	v_cvt_pk_bf16_f32 v90, v80, v81
	v_cvt_pk_bf16_f32 v91, v84, v85
	s_mov_b32 vcc_lo, 0xff00ff00
	s_mov_b32 vcc_hi, 0xff00ff00
	v_mov_b32_dpp v222, v218 row_ror:8 row_mask:0xf bank_mask:0xf
	v_mov_b32_dpp v223, v219 row_ror:8 row_mask:0xf bank_mask:0xf
	v_mov_b32_dpp v224, v220 row_ror:8 row_mask:0xf bank_mask:0xf
	v_mov_b32_dpp v225, v221 row_ror:8 row_mask:0xf bank_mask:0xf
	v_mov_b32_dpp v242, v88 row_ror:8 row_mask:0xf bank_mask:0xf
	v_mov_b32_dpp v243, v89 row_ror:8 row_mask:0xf bank_mask:0xf
	v_mov_b32_dpp v244, v90 row_ror:8 row_mask:0xf bank_mask:0xf
	v_mov_b32_dpp v245, v91 row_ror:8 row_mask:0xf bank_mask:0xf
	v_lshl_add_u64 v[246:247], v[208:209], 0, v[214:215]
	v_lshl_add_u64 v[248:249], v[208:209], 0, v[216:217]
	v_cndmask_b32_e32 v242, v218, v242, vcc
	v_cndmask_b32_e32 v243, v219, v243, vcc
	v_cndmask_b32_e32 v244, v220, v244, vcc
	v_cndmask_b32_e32 v245, v221, v245, vcc
	v_cndmask_b32_e32 v222, v222, v88, vcc
	v_cndmask_b32_e32 v223, v223, v89, vcc
	v_cndmask_b32_e32 v224, v224, v90, vcc
	v_cndmask_b32_e32 v225, v225, v91, vcc
	global_store_dwordx4 v[246:247], v[242:245], off nt
	global_store_dwordx4 v[248:249], v[222:225], off nt
	s_branch .LBB0_359
